# grid-barrier spin loops poll without the 64-cycle sleep (s_sleep 0), on v24
# speedup vs baseline: 1.0025x; 1.0025x over previous
.LBB0_11:
	s_sleep 0
	global_load_dword v2, v0, s[6:7] offset:32 sc1
	s_waitcnt vmcnt(0)
	v_and_b32_e32 v2, 0xffff0000, v2
	v_cmp_ne_u32_e32 vcc, v2, v1
	s_or_b64 s[8:9], vcc, s[8:9]
	s_andn2_b64 exec, exec, s[8:9]
	s_cbranch_execnz .LBB0_11

.LBB0_215:
	global_load_dword v15, v16, s[10:11] sc1
	s_waitcnt lgkmcnt(0)
	global_load_dword v0, v16, s[12:13] sc1
	global_load_dword v1, v16, s[14:15] sc1
	global_load_dword v2, v16, s[16:17] sc1
	global_load_dword v3, v16, s[18:19] sc1
	global_load_dword v4, v16, s[20:21] sc1
	global_load_dword v5, v16, s[22:23] sc1
	global_load_dword v6, v16, s[24:25] sc1
	global_load_dword v7, v16, s[26:27] sc1
	global_load_dword v8, v16, s[28:29] sc1
	global_load_dword v9, v16, s[30:31] sc1
	global_load_dword v10, v16, s[34:35] sc1
	global_load_dword v11, v16, s[36:37] sc1
	global_load_dword v12, v16, s[38:39] sc1
	global_load_dword v13, v16, s[40:41] sc1
	global_load_dword v14, v16, s[42:43] sc1
	s_mov_b64 s[44:45], -1
	s_mov_b64 s[46:47], -1
	s_waitcnt vmcnt(14)
	v_add_u32_e32 v17, v0, v15
	s_waitcnt vmcnt(13)
	v_add_u32_e32 v17, v17, v1
	s_waitcnt vmcnt(12)
	v_add_u32_e32 v17, v17, v2
	s_waitcnt vmcnt(11)
	v_add_u32_e32 v17, v17, v3
	s_waitcnt vmcnt(10)
	v_add_u32_e32 v17, v17, v4
	s_waitcnt vmcnt(9)
	v_add_u32_e32 v17, v17, v5
	s_waitcnt vmcnt(8)
	v_add_u32_e32 v17, v17, v6
	s_waitcnt vmcnt(7)
	v_add_u32_e32 v17, v17, v7
	s_waitcnt vmcnt(6)
	v_add_u32_e32 v17, v17, v8
	s_waitcnt vmcnt(5)
	v_add_u32_e32 v17, v17, v9
	s_waitcnt vmcnt(4)
	v_add_u32_e32 v17, v17, v10
	s_waitcnt vmcnt(3)
	v_add_u32_e32 v17, v17, v11
	s_waitcnt vmcnt(2)
	v_add_u32_e32 v17, v17, v12
	s_waitcnt vmcnt(1)
	v_add_u32_e32 v17, v17, v13
	s_waitcnt vmcnt(0)
	v_add_u32_e32 v17, v17, v14
	v_cmp_eq_u32_e32 vcc, s1, v17
	s_cbranch_vccnz .LBB0_214
	s_and_b32 s3, s2, 0xff
	s_cmp_eq_u32 s3, 0
	s_mov_b64 s[48:49], -1
	s_sleep 0
	s_cbranch_scc0 .LBB0_219
	global_load_dword v17, v16, s[8:9] sc1
	s_waitcnt vmcnt(0)
	v_cmp_eq_u32_e32 vcc, 0, v17
	s_cbranch_vccnz .LBB0_221
	s_mov_b64 s[48:49], 0

.LBB0_233:
	s_and_b32 s2, s1, 0xff
	s_mov_b64 s[20:21], -1
	s_cmp_lg_u32 s2, 0
	s_mov_b64 s[24:25], -1
	s_sleep 0
	s_cbranch_scc1 .LBB0_236
	global_load_dword v2, v0, s[12:13] sc1
	s_waitcnt vmcnt(0)
	v_cmp_eq_u32_e32 vcc, 0, v2
	s_cbranch_vccnz .LBB0_238
	s_mov_b64 s[24:25], 0
	s_mov_b64 s[22:23], -1

.LBB0_250:
	s_and_b32 s2, s1, 0xff
	s_cmp_lg_u32 s2, 0
	s_mov_b64 s[22:23], -1
	s_sleep 0
	s_cbranch_scc1 .LBB0_253
	global_load_dword v1, v0, s[12:13] sc1
	s_waitcnt vmcnt(0)
	v_cmp_eq_u32_e32 vcc, 0, v1
	s_cbranch_vccnz .LBB0_255
	s_mov_b64 s[22:23], 0
	s_mov_b64 s[20:21], -1

.LBB0_1561:
	v_readlane_b32 s6, v253, 22
	v_readlane_b32 s7, v253, 23
	s_mov_b64 s[8:9], -1
	s_nop 3
	global_load_dword v0, v193, s[6:7] sc1
	v_readlane_b32 s6, v253, 24
	v_readlane_b32 s7, v253, 25
	s_nop 4
	global_load_dword v1, v193, s[6:7] sc1
	v_readlane_b32 s6, v253, 26
	v_readlane_b32 s7, v253, 27
	s_waitcnt vmcnt(0)
	v_add_u32_e32 v16, v1, v0
	s_nop 2
	global_load_dword v2, v193, s[6:7] sc1
	v_readlane_b32 s6, v253, 28
	v_readlane_b32 s7, v253, 29
	s_waitcnt vmcnt(0)
	v_add_u32_e32 v16, v16, v2
	s_nop 2
	global_load_dword v3, v193, s[6:7] sc1
	v_readlane_b32 s6, v253, 30
	v_readlane_b32 s7, v253, 31
	s_waitcnt vmcnt(0)
	v_add_u32_e32 v16, v16, v3
	s_nop 2
	global_load_dword v4, v193, s[6:7] sc1
	v_readlane_b32 s6, v253, 32
	v_readlane_b32 s7, v253, 33
	s_waitcnt vmcnt(0)
	v_add_u32_e32 v16, v16, v4
	s_nop 2
	global_load_dword v5, v193, s[6:7] sc1
	v_readlane_b32 s6, v253, 34
	v_readlane_b32 s7, v253, 35
	s_waitcnt vmcnt(0)
	v_add_u32_e32 v16, v16, v5
	s_nop 2
	global_load_dword v6, v193, s[6:7] sc1
	v_readlane_b32 s6, v253, 36
	v_readlane_b32 s7, v253, 37
	s_waitcnt vmcnt(0)
	v_add_u32_e32 v16, v16, v6
	s_nop 2
	global_load_dword v7, v193, s[6:7] sc1
	v_readlane_b32 s6, v253, 38
	v_readlane_b32 s7, v253, 39
	s_waitcnt vmcnt(0)
	v_add_u32_e32 v16, v16, v7
	s_nop 2
	global_load_dword v8, v193, s[6:7] sc1
	v_readlane_b32 s6, v253, 40
	v_readlane_b32 s7, v253, 41
	s_waitcnt vmcnt(0)
	v_add_u32_e32 v16, v16, v8
	s_nop 2
	global_load_dword v9, v193, s[6:7] sc1
	v_readlane_b32 s6, v253, 42
	v_readlane_b32 s7, v253, 43
	s_waitcnt vmcnt(0)
	v_add_u32_e32 v16, v16, v9
	s_nop 2
	global_load_dword v10, v193, s[6:7] sc1
	v_readlane_b32 s6, v253, 44
	v_readlane_b32 s7, v253, 45
	s_waitcnt vmcnt(0)
	v_add_u32_e32 v16, v16, v10
	s_nop 2
	global_load_dword v11, v193, s[6:7] sc1
	v_readlane_b32 s6, v253, 46
	v_readlane_b32 s7, v253, 47
	s_waitcnt vmcnt(0)
	v_add_u32_e32 v16, v16, v11
	s_nop 2
	global_load_dword v12, v193, s[6:7] sc1
	v_readlane_b32 s6, v253, 48
	v_readlane_b32 s7, v253, 49
	s_waitcnt vmcnt(0)
	v_add_u32_e32 v16, v16, v12
	s_nop 2
	global_load_dword v13, v193, s[6:7] sc1
	v_readlane_b32 s6, v253, 50
	v_readlane_b32 s7, v253, 51
	s_waitcnt vmcnt(0)
	v_add_u32_e32 v16, v16, v13
	s_nop 2
	global_load_dword v14, v193, s[6:7] sc1
	v_readlane_b32 s6, v253, 52
	v_readlane_b32 s7, v253, 53
	s_waitcnt vmcnt(0)
	v_add_u32_e32 v16, v16, v14
	s_nop 2
	global_load_dword v15, v193, s[6:7] sc1
	s_mov_b64 s[6:7], -1
	s_waitcnt vmcnt(0)
	v_add_u32_e32 v16, v16, v15
	v_cmp_eq_u32_e32 vcc, s12, v16
	s_cbranch_vccnz .LBB0_1560
	s_and_b32 s6, s13, 0xff
	s_cmp_eq_u32 s6, 0
	s_mov_b64 s[6:7], -1
	s_mov_b64 s[10:11], -1
	s_sleep 0
	s_cbranch_scc0 .LBB0_1565
	v_readlane_b32 s6, v253, 20
	v_readlane_b32 s7, v253, 21
	s_nop 4
	global_load_dword v16, v193, s[6:7] sc1
	s_waitcnt vmcnt(0)
	v_cmp_eq_u32_e32 vcc, 0, v16
	s_cbranch_vccnz .LBB0_1567
	s_mov_b64 s[10:11], 0
	s_mov_b64 s[6:7], -1

.LBB0_1579:
	s_and_b32 s18, s1, 0xff
	s_mov_b64 s[16:17], -1
	s_cmp_lg_u32 s18, 0
	s_mov_b64 s[20:21], -1
	s_sleep 0
	s_cbranch_scc1 .LBB0_1582
	v_readlane_b32 s18, v253, 20
	v_readlane_b32 s19, v253, 21
	s_nop 4
	global_load_dword v0, v193, s[18:19] sc1
	s_waitcnt vmcnt(0)
	v_cmp_eq_u32_e32 vcc, 0, v0
	s_cbranch_vccnz .LBB0_1584
	s_mov_b64 s[20:21], 0
	s_mov_b64 s[18:19], -1

.LBB0_1596:
	s_and_b32 s16, s1, 0xff
	s_mov_b64 s[14:15], -1
	s_cmp_lg_u32 s16, 0
	s_mov_b64 s[18:19], -1
	s_sleep 0
	s_cbranch_scc1 .LBB0_1599
	v_readlane_b32 s16, v253, 20
	v_readlane_b32 s17, v253, 21
	s_nop 4
	global_load_dword v0, v193, s[16:17] sc1
	s_waitcnt vmcnt(0)
	v_cmp_eq_u32_e32 vcc, 0, v0
	s_cbranch_vccnz .LBB0_1601
	s_mov_b64 s[18:19], 0
	s_mov_b64 s[16:17], -1

.LBB0_2107:
	s_and_b32 s20, s1, 0xff
	s_mov_b64 s[18:19], -1
	s_cmp_lg_u32 s20, 0
	s_mov_b64 s[22:23], -1
	s_sleep 0
	s_cbranch_scc1 .LBB0_2110
	v_readlane_b32 s20, v253, 20
	v_readlane_b32 s21, v253, 21
	s_nop 4
	global_load_dword v0, v193, s[20:21] sc1
	s_waitcnt vmcnt(0)
	v_cmp_eq_u32_e32 vcc, 0, v0
	s_cbranch_vccnz .LBB0_2112
	s_mov_b64 s[22:23], 0
	s_mov_b64 s[20:21], -1

.LBB0_2124:
	s_and_b32 s18, s1, 0xff
	s_mov_b64 s[14:15], -1
	s_cmp_lg_u32 s18, 0
	s_mov_b64 s[20:21], -1
	s_sleep 0
	s_cbranch_scc1 .LBB0_2127
	v_readlane_b32 s18, v253, 20
	v_readlane_b32 s19, v253, 21
	s_nop 4
	global_load_dword v0, v193, s[18:19] sc1
	s_waitcnt vmcnt(0)
	v_cmp_eq_u32_e32 vcc, 0, v0
	s_cbranch_vccnz .LBB0_2129
	s_mov_b64 s[20:21], 0
	s_mov_b64 s[18:19], -1

.LBB0_2221:
	v_readlane_b32 s8, v253, 22
	v_readlane_b32 s9, v253, 23
	v_readlane_b32 s12, v253, 60
	s_waitcnt lgkmcnt(0)
	s_nop 2
	global_load_dword v0, v193, s[8:9] sc1
	v_readlane_b32 s8, v253, 24
	v_readlane_b32 s9, v253, 25
	s_nop 4
	global_load_dword v1, v193, s[8:9] sc1
	v_readlane_b32 s8, v253, 26
	v_readlane_b32 s9, v253, 27
	s_waitcnt vmcnt(0)
	v_add_u32_e32 v16, v1, v0
	s_nop 2
	global_load_dword v2, v193, s[8:9] sc1
	v_readlane_b32 s8, v253, 28
	v_readlane_b32 s9, v253, 29
	s_waitcnt vmcnt(0)
	v_add_u32_e32 v16, v16, v2
	s_nop 2
	global_load_dword v3, v193, s[8:9] sc1
	v_readlane_b32 s8, v253, 30
	v_readlane_b32 s9, v253, 31
	s_waitcnt vmcnt(0)
	v_add_u32_e32 v16, v16, v3
	s_nop 2
	global_load_dword v4, v193, s[8:9] sc1
	v_readlane_b32 s8, v253, 32
	v_readlane_b32 s9, v253, 33
	s_waitcnt vmcnt(0)
	v_add_u32_e32 v16, v16, v4
	s_nop 2
	global_load_dword v5, v193, s[8:9] sc1
	v_readlane_b32 s8, v253, 34
	v_readlane_b32 s9, v253, 35
	s_waitcnt vmcnt(0)
	v_add_u32_e32 v16, v16, v5
	s_nop 2
	global_load_dword v6, v193, s[8:9] sc1
	v_readlane_b32 s8, v253, 36
	v_readlane_b32 s9, v253, 37
	s_waitcnt vmcnt(0)
	v_add_u32_e32 v16, v16, v6
	s_nop 2
	global_load_dword v7, v193, s[8:9] sc1
	v_readlane_b32 s8, v253, 38
	v_readlane_b32 s9, v253, 39
	s_waitcnt vmcnt(0)
	v_add_u32_e32 v16, v16, v7
	s_nop 2
	global_load_dword v8, v193, s[8:9] sc1
	v_readlane_b32 s8, v253, 40
	v_readlane_b32 s9, v253, 41
	s_waitcnt vmcnt(0)
	v_add_u32_e32 v16, v16, v8
	s_nop 2
	global_load_dword v9, v193, s[8:9] sc1
	v_readlane_b32 s8, v253, 42
	v_readlane_b32 s9, v253, 43
	s_waitcnt vmcnt(0)
	v_add_u32_e32 v16, v16, v9
	s_nop 2
	global_load_dword v10, v193, s[8:9] sc1
	v_readlane_b32 s8, v253, 44
	v_readlane_b32 s9, v253, 45
	s_waitcnt vmcnt(0)
	v_add_u32_e32 v16, v16, v10
	s_nop 2
	global_load_dword v11, v193, s[8:9] sc1
	v_readlane_b32 s8, v253, 46
	v_readlane_b32 s9, v253, 47
	s_waitcnt vmcnt(0)
	v_add_u32_e32 v16, v16, v11
	s_nop 2
	global_load_dword v12, v193, s[8:9] sc1
	v_readlane_b32 s8, v253, 48
	v_readlane_b32 s9, v253, 49
	s_waitcnt vmcnt(0)
	v_add_u32_e32 v16, v16, v12
	s_nop 2
	global_load_dword v13, v193, s[8:9] sc1
	v_readlane_b32 s8, v253, 50
	v_readlane_b32 s9, v253, 51
	s_waitcnt vmcnt(0)
	v_add_u32_e32 v16, v16, v13
	s_nop 2
	global_load_dword v14, v193, s[8:9] sc1
	v_readlane_b32 s8, v253, 52
	v_readlane_b32 s9, v253, 53
	s_waitcnt vmcnt(0)
	v_add_u32_e32 v16, v16, v14
	s_nop 2
	global_load_dword v15, v193, s[8:9] sc1
	s_mov_b64 s[8:9], -1
	s_waitcnt vmcnt(0)
	v_add_u32_e32 v16, v16, v15
	v_cmp_eq_u32_e32 vcc, s12, v16
	s_mov_b64 s[12:13], -1
	s_cbranch_vccnz .LBB0_2220
	s_and_b32 s8, s17, 0xff
	s_cmp_eq_u32 s8, 0
	s_mov_b64 s[8:9], -1
	s_mov_b64 s[14:15], -1
	s_sleep 0
	s_cbranch_scc0 .LBB0_2225
	v_readlane_b32 s8, v253, 20
	v_readlane_b32 s9, v253, 21
	s_nop 4
	global_load_dword v16, v193, s[8:9] sc1
	s_waitcnt vmcnt(0)
	v_cmp_eq_u32_e32 vcc, 0, v16
	s_cbranch_vccnz .LBB0_2227
	s_mov_b64 s[14:15], 0
	s_mov_b64 s[8:9], -1

.LBB0_2248:
	s_and_b32 s17, s1, 0xff
	s_mov_b64 s[26:27], -1
	s_cmp_lg_u32 s17, 0
	s_mov_b64 s[30:31], -1
	s_sleep 0
	s_cbranch_scc1 .LBB0_2251
	v_readlane_b32 s28, v253, 20
	v_readlane_b32 s29, v253, 21
	s_nop 4
	global_load_dword v0, v193, s[28:29] sc1
	s_waitcnt vmcnt(0)
	v_cmp_eq_u32_e32 vcc, 0, v0
	s_cbranch_vccnz .LBB0_2253
	s_mov_b64 s[30:31], 0
	s_mov_b64 s[28:29], -1

.LBB0_2265:
	s_and_b32 s17, s1, 0xff
	s_mov_b64 s[24:25], -1
	s_cmp_lg_u32 s17, 0
	s_mov_b64 s[28:29], -1
	s_sleep 0
	s_cbranch_scc1 .LBB0_2268
	v_readlane_b32 s26, v253, 20
	v_readlane_b32 s27, v253, 21
	s_nop 4
	global_load_dword v0, v193, s[26:27] sc1
	s_waitcnt vmcnt(0)
	v_cmp_eq_u32_e32 vcc, 0, v0
	s_cbranch_vccnz .LBB0_2270
	s_mov_b64 s[28:29], 0
	s_mov_b64 s[26:27], -1

.LBB0_2333:
	v_readlane_b32 s8, v253, 22
	v_readlane_b32 s9, v253, 23
	v_readlane_b32 s10, v253, 60
	s_waitcnt lgkmcnt(0)
	s_nop 2
	global_load_dword v0, v193, s[8:9] sc1
	v_readlane_b32 s8, v253, 24
	v_readlane_b32 s9, v253, 25
	s_nop 4
	global_load_dword v1, v193, s[8:9] sc1
	v_readlane_b32 s8, v253, 26
	v_readlane_b32 s9, v253, 27
	s_waitcnt vmcnt(0)
	v_add_u32_e32 v16, v1, v0
	s_nop 2
	global_load_dword v2, v193, s[8:9] sc1
	v_readlane_b32 s8, v253, 28
	v_readlane_b32 s9, v253, 29
	s_waitcnt vmcnt(0)
	v_add_u32_e32 v16, v16, v2
	s_nop 2
	global_load_dword v3, v193, s[8:9] sc1
	v_readlane_b32 s8, v253, 30
	v_readlane_b32 s9, v253, 31
	s_waitcnt vmcnt(0)
	v_add_u32_e32 v16, v16, v3
	s_nop 2
	global_load_dword v4, v193, s[8:9] sc1
	v_readlane_b32 s8, v253, 32
	v_readlane_b32 s9, v253, 33
	s_waitcnt vmcnt(0)
	v_add_u32_e32 v16, v16, v4
	s_nop 2
	global_load_dword v5, v193, s[8:9] sc1
	v_readlane_b32 s8, v253, 34
	v_readlane_b32 s9, v253, 35
	s_waitcnt vmcnt(0)
	v_add_u32_e32 v16, v16, v5
	s_nop 2
	global_load_dword v6, v193, s[8:9] sc1
	v_readlane_b32 s8, v253, 36
	v_readlane_b32 s9, v253, 37
	s_waitcnt vmcnt(0)
	v_add_u32_e32 v16, v16, v6
	s_nop 2
	global_load_dword v7, v193, s[8:9] sc1
	v_readlane_b32 s8, v253, 38
	v_readlane_b32 s9, v253, 39
	s_waitcnt vmcnt(0)
	v_add_u32_e32 v16, v16, v7
	s_nop 2
	global_load_dword v8, v193, s[8:9] sc1
	v_readlane_b32 s8, v253, 40
	v_readlane_b32 s9, v253, 41
	s_waitcnt vmcnt(0)
	v_add_u32_e32 v16, v16, v8
	s_nop 2
	global_load_dword v9, v193, s[8:9] sc1
	v_readlane_b32 s8, v253, 42
	v_readlane_b32 s9, v253, 43
	s_waitcnt vmcnt(0)
	v_add_u32_e32 v16, v16, v9
	s_nop 2
	global_load_dword v10, v193, s[8:9] sc1
	v_readlane_b32 s8, v253, 44
	v_readlane_b32 s9, v253, 45
	s_waitcnt vmcnt(0)
	v_add_u32_e32 v16, v16, v10
	s_nop 2
	global_load_dword v11, v193, s[8:9] sc1
	v_readlane_b32 s8, v253, 46
	v_readlane_b32 s9, v253, 47
	s_waitcnt vmcnt(0)
	v_add_u32_e32 v16, v16, v11
	s_nop 2
	global_load_dword v12, v193, s[8:9] sc1
	v_readlane_b32 s8, v253, 48
	v_readlane_b32 s9, v253, 49
	s_waitcnt vmcnt(0)
	v_add_u32_e32 v16, v16, v12
	s_nop 2
	global_load_dword v13, v193, s[8:9] sc1
	v_readlane_b32 s8, v253, 50
	v_readlane_b32 s9, v253, 51
	s_waitcnt vmcnt(0)
	v_add_u32_e32 v16, v16, v13
	s_nop 2
	global_load_dword v14, v193, s[8:9] sc1
	v_readlane_b32 s8, v253, 52
	v_readlane_b32 s9, v253, 53
	s_waitcnt vmcnt(0)
	v_add_u32_e32 v16, v16, v14
	s_nop 2
	global_load_dword v15, v193, s[8:9] sc1
	s_mov_b64 s[8:9], -1
	s_waitcnt vmcnt(0)
	v_add_u32_e32 v16, v16, v15
	v_cmp_eq_u32_e32 vcc, s10, v16
	s_mov_b64 s[10:11], -1
	s_cbranch_vccnz .LBB0_2332
	s_and_b32 s8, s14, 0xff
	s_cmp_eq_u32 s8, 0
	s_mov_b64 s[8:9], -1
	s_mov_b64 s[12:13], -1
	s_sleep 0
	s_cbranch_scc0 .LBB0_2337
	v_readlane_b32 s8, v253, 20
	v_readlane_b32 s9, v253, 21
	s_nop 4
	global_load_dword v16, v193, s[8:9] sc1
	s_waitcnt vmcnt(0)
	v_cmp_eq_u32_e32 vcc, 0, v16
	s_cbranch_vccnz .LBB0_2339
	s_mov_b64 s[12:13], 0
	s_mov_b64 s[8:9], -1

.LBB0_2375:
	s_and_b32 s17, s1, 0xff
	s_mov_b64 s[22:23], -1
	s_cmp_lg_u32 s17, 0
	s_mov_b64 s[26:27], -1
	s_sleep 0
	s_cbranch_scc1 .LBB0_2378
	v_readlane_b32 s24, v253, 20
	v_readlane_b32 s25, v253, 21
	s_nop 4
	global_load_dword v0, v193, s[24:25] sc1
	s_waitcnt vmcnt(0)
	v_cmp_eq_u32_e32 vcc, 0, v0
	s_cbranch_vccnz .LBB0_2380
	s_mov_b64 s[26:27], 0
	s_mov_b64 s[24:25], -1

.LBB0_2525:
	v_readlane_b32 s6, v253, 22
	v_readlane_b32 s7, v253, 23
	v_readlane_b32 s8, v253, 60
	s_waitcnt lgkmcnt(0)
	s_nop 2
	global_load_dword v0, v193, s[6:7] sc1
	v_readlane_b32 s6, v253, 24
	v_readlane_b32 s7, v253, 25
	s_nop 4
	global_load_dword v1, v193, s[6:7] sc1
	v_readlane_b32 s6, v253, 26
	v_readlane_b32 s7, v253, 27
	s_waitcnt vmcnt(0)
	v_add_u32_e32 v16, v1, v0
	s_nop 2
	global_load_dword v2, v193, s[6:7] sc1
	v_readlane_b32 s6, v253, 28
	v_readlane_b32 s7, v253, 29
	s_waitcnt vmcnt(0)
	v_add_u32_e32 v16, v16, v2
	s_nop 2
	global_load_dword v3, v193, s[6:7] sc1
	v_readlane_b32 s6, v253, 30
	v_readlane_b32 s7, v253, 31
	s_waitcnt vmcnt(0)
	v_add_u32_e32 v16, v16, v3
	s_nop 2
	global_load_dword v4, v193, s[6:7] sc1
	v_readlane_b32 s6, v253, 32
	v_readlane_b32 s7, v253, 33
	s_waitcnt vmcnt(0)
	v_add_u32_e32 v16, v16, v4
	s_nop 2
	global_load_dword v5, v193, s[6:7] sc1
	v_readlane_b32 s6, v253, 34
	v_readlane_b32 s7, v253, 35
	s_waitcnt vmcnt(0)
	v_add_u32_e32 v16, v16, v5
	s_nop 2
	global_load_dword v6, v193, s[6:7] sc1
	v_readlane_b32 s6, v253, 36
	v_readlane_b32 s7, v253, 37
	s_waitcnt vmcnt(0)
	v_add_u32_e32 v16, v16, v6
	s_nop 2
	global_load_dword v7, v193, s[6:7] sc1
	v_readlane_b32 s6, v253, 38
	v_readlane_b32 s7, v253, 39
	s_waitcnt vmcnt(0)
	v_add_u32_e32 v16, v16, v7
	s_nop 2
	global_load_dword v8, v193, s[6:7] sc1
	v_readlane_b32 s6, v253, 40
	v_readlane_b32 s7, v253, 41
	s_waitcnt vmcnt(0)
	v_add_u32_e32 v16, v16, v8
	s_nop 2
	global_load_dword v9, v193, s[6:7] sc1
	v_readlane_b32 s6, v253, 42
	v_readlane_b32 s7, v253, 43
	s_waitcnt vmcnt(0)
	v_add_u32_e32 v16, v16, v9
	s_nop 2
	global_load_dword v10, v193, s[6:7] sc1
	v_readlane_b32 s6, v253, 44
	v_readlane_b32 s7, v253, 45
	s_waitcnt vmcnt(0)
	v_add_u32_e32 v16, v16, v10
	s_nop 2
	global_load_dword v11, v193, s[6:7] sc1
	v_readlane_b32 s6, v253, 46
	v_readlane_b32 s7, v253, 47
	s_waitcnt vmcnt(0)
	v_add_u32_e32 v16, v16, v11
	s_nop 2
	global_load_dword v12, v193, s[6:7] sc1
	v_readlane_b32 s6, v253, 48
	v_readlane_b32 s7, v253, 49
	s_waitcnt vmcnt(0)
	v_add_u32_e32 v16, v16, v12
	s_nop 2
	global_load_dword v13, v193, s[6:7] sc1
	v_readlane_b32 s6, v253, 50
	v_readlane_b32 s7, v253, 51
	s_waitcnt vmcnt(0)
	v_add_u32_e32 v16, v16, v13
	s_nop 2
	global_load_dword v14, v193, s[6:7] sc1
	v_readlane_b32 s6, v253, 52
	v_readlane_b32 s7, v253, 53
	s_waitcnt vmcnt(0)
	v_add_u32_e32 v16, v16, v14
	s_nop 2
	global_load_dword v15, v193, s[6:7] sc1
	s_mov_b64 s[6:7], -1
	s_waitcnt vmcnt(0)
	v_add_u32_e32 v16, v16, v15
	v_cmp_eq_u32_e32 vcc, s8, v16
	s_mov_b64 s[8:9], -1
	s_cbranch_vccnz .LBB0_2524
	s_and_b32 s6, s12, 0xff
	s_cmp_eq_u32 s6, 0
	s_mov_b64 s[6:7], -1
	s_mov_b64 s[10:11], -1
	s_sleep 0
	s_cbranch_scc0 .LBB0_2529
	v_readlane_b32 s6, v253, 20
	v_readlane_b32 s7, v253, 21
	s_nop 4
	global_load_dword v16, v193, s[6:7] sc1
	s_waitcnt vmcnt(0)
	v_cmp_eq_u32_e32 vcc, 0, v16
	s_cbranch_vccnz .LBB0_2531
	s_mov_b64 s[10:11], 0
	s_mov_b64 s[6:7], -1

.LBB0_2552:
	s_and_b32 s17, s1, 0xff
	s_mov_b64 s[18:19], -1
	s_cmp_lg_u32 s17, 0
	s_mov_b64 s[22:23], -1
	s_sleep 0
	s_cbranch_scc1 .LBB0_2555
	v_readlane_b32 s20, v253, 20
	v_readlane_b32 s21, v253, 21
	s_nop 4
	global_load_dword v0, v193, s[20:21] sc1
	s_waitcnt vmcnt(0)
	v_cmp_eq_u32_e32 vcc, 0, v0
	s_cbranch_vccnz .LBB0_2557
	s_mov_b64 s[22:23], 0
	s_mov_b64 s[20:21], -1

.LBB0_2569:
	s_and_b32 s17, s1, 0xff
	s_mov_b64 s[14:15], -1
	s_cmp_lg_u32 s17, 0
	s_mov_b64 s[20:21], -1
	s_sleep 0
	s_cbranch_scc1 .LBB0_2572
	v_readlane_b32 s18, v253, 20
	v_readlane_b32 s19, v253, 21
	s_nop 4
	global_load_dword v0, v193, s[18:19] sc1
	s_waitcnt vmcnt(0)
	v_cmp_eq_u32_e32 vcc, 0, v0
	s_cbranch_vccnz .LBB0_2574
	s_mov_b64 s[20:21], 0
	s_mov_b64 s[18:19], -1

.LBB0_3556:
	v_readlane_b32 s4, v253, 22
	v_readlane_b32 s5, v253, 23
	v_readlane_b32 s6, v253, 60
	s_waitcnt lgkmcnt(0)
	s_nop 2
	global_load_dword v0, v193, s[4:5] sc1
	v_readlane_b32 s4, v253, 24
	v_readlane_b32 s5, v253, 25
	s_nop 4
	global_load_dword v1, v193, s[4:5] sc1
	v_readlane_b32 s4, v253, 26
	v_readlane_b32 s5, v253, 27
	s_waitcnt vmcnt(0)
	v_add_u32_e32 v16, v1, v0
	s_nop 2
	global_load_dword v2, v193, s[4:5] sc1
	v_readlane_b32 s4, v253, 28
	v_readlane_b32 s5, v253, 29
	s_waitcnt vmcnt(0)
	v_add_u32_e32 v16, v16, v2
	s_nop 2
	global_load_dword v3, v193, s[4:5] sc1
	v_readlane_b32 s4, v253, 30
	v_readlane_b32 s5, v253, 31
	s_waitcnt vmcnt(0)
	v_add_u32_e32 v16, v16, v3
	s_nop 2
	global_load_dword v4, v193, s[4:5] sc1
	v_readlane_b32 s4, v253, 32
	v_readlane_b32 s5, v253, 33
	s_waitcnt vmcnt(0)
	v_add_u32_e32 v16, v16, v4
	s_nop 2
	global_load_dword v5, v193, s[4:5] sc1
	v_readlane_b32 s4, v253, 34
	v_readlane_b32 s5, v253, 35
	s_waitcnt vmcnt(0)
	v_add_u32_e32 v16, v16, v5
	s_nop 2
	global_load_dword v6, v193, s[4:5] sc1
	v_readlane_b32 s4, v253, 36
	v_readlane_b32 s5, v253, 37
	s_waitcnt vmcnt(0)
	v_add_u32_e32 v16, v16, v6
	s_nop 2
	global_load_dword v7, v193, s[4:5] sc1
	v_readlane_b32 s4, v253, 38
	v_readlane_b32 s5, v253, 39
	s_waitcnt vmcnt(0)
	v_add_u32_e32 v16, v16, v7
	s_nop 2
	global_load_dword v8, v193, s[4:5] sc1
	v_readlane_b32 s4, v253, 40
	v_readlane_b32 s5, v253, 41
	s_waitcnt vmcnt(0)
	v_add_u32_e32 v16, v16, v8
	s_nop 2
	global_load_dword v9, v193, s[4:5] sc1
	v_readlane_b32 s4, v253, 42
	v_readlane_b32 s5, v253, 43
	s_waitcnt vmcnt(0)
	v_add_u32_e32 v16, v16, v9
	s_nop 2
	global_load_dword v10, v193, s[4:5] sc1
	v_readlane_b32 s4, v253, 44
	v_readlane_b32 s5, v253, 45
	s_waitcnt vmcnt(0)
	v_add_u32_e32 v16, v16, v10
	s_nop 2
	global_load_dword v11, v193, s[4:5] sc1
	v_readlane_b32 s4, v253, 46
	v_readlane_b32 s5, v253, 47
	s_waitcnt vmcnt(0)
	v_add_u32_e32 v16, v16, v11
	s_nop 2
	global_load_dword v12, v193, s[4:5] sc1
	v_readlane_b32 s4, v253, 48
	v_readlane_b32 s5, v253, 49
	s_waitcnt vmcnt(0)
	v_add_u32_e32 v16, v16, v12
	s_nop 2
	global_load_dword v13, v193, s[4:5] sc1
	v_readlane_b32 s4, v253, 50
	v_readlane_b32 s5, v253, 51
	s_waitcnt vmcnt(0)
	v_add_u32_e32 v16, v16, v13
	s_nop 2
	global_load_dword v14, v193, s[4:5] sc1
	v_readlane_b32 s4, v253, 52
	v_readlane_b32 s5, v253, 53
	s_waitcnt vmcnt(0)
	v_add_u32_e32 v16, v16, v14
	s_nop 2
	global_load_dword v15, v193, s[4:5] sc1
	s_mov_b64 s[4:5], -1
	s_waitcnt vmcnt(0)
	v_add_u32_e32 v16, v16, v15
	v_cmp_eq_u32_e32 vcc, s6, v16
	s_mov_b64 s[6:7], -1
	s_cbranch_vccnz .LBB0_3555
	s_and_b32 s4, s12, 0xff
	s_cmp_eq_u32 s4, 0
	s_mov_b64 s[4:5], -1
	s_mov_b64 s[8:9], -1
	s_sleep 0
	s_cbranch_scc0 .LBB0_3560
	v_readlane_b32 s4, v253, 20
	v_readlane_b32 s5, v253, 21
	s_nop 4
	global_load_dword v16, v193, s[4:5] sc1
	s_waitcnt vmcnt(0)
	v_cmp_eq_u32_e32 vcc, 0, v16
	s_cbranch_vccnz .LBB0_3562
	s_mov_b64 s[8:9], 0
	s_mov_b64 s[4:5], -1

.LBB0_3574:
	s_and_b32 s16, s21, 0xff
	s_mov_b64 s[14:15], -1
	s_cmp_lg_u32 s16, 0
	s_mov_b64 s[18:19], -1
	s_sleep 0
	s_cbranch_scc1 .LBB0_3577
	v_readlane_b32 s16, v253, 20
	v_readlane_b32 s17, v253, 21
	s_nop 4
	global_load_dword v0, v193, s[16:17] sc1
	s_waitcnt vmcnt(0)
	v_cmp_eq_u32_e32 vcc, 0, v0
	s_cbranch_vccnz .LBB0_3579
	s_mov_b64 s[18:19], 0
	s_mov_b64 s[16:17], -1

.LBB0_3591:
	s_and_b32 s14, s18, 0xff
	s_mov_b64 s[12:13], -1
	s_cmp_lg_u32 s14, 0
	s_mov_b64 s[16:17], -1
	s_sleep 0
	s_cbranch_scc1 .LBB0_3594
	v_readlane_b32 s14, v253, 20
	v_readlane_b32 s15, v253, 21
	s_nop 4
	global_load_dword v0, v193, s[14:15] sc1
	s_waitcnt vmcnt(0)
	v_cmp_eq_u32_e32 vcc, 0, v0
	s_cbranch_vccnz .LBB0_3596
	s_mov_b64 s[16:17], 0
	s_mov_b64 s[14:15], -1

.LBB0_3668:
	v_readlane_b32 s4, v253, 22
	v_readlane_b32 s5, v253, 23
	s_mov_b64 s[6:7], -1
	s_nop 3
	global_load_dword v0, v193, s[4:5] sc1
	v_readlane_b32 s4, v253, 24
	v_readlane_b32 s5, v253, 25
	s_nop 4
	global_load_dword v1, v193, s[4:5] sc1
	v_readlane_b32 s4, v253, 26
	v_readlane_b32 s5, v253, 27
	s_waitcnt vmcnt(0)
	v_add_u32_e32 v16, v1, v0
	s_nop 2
	global_load_dword v2, v193, s[4:5] sc1
	v_readlane_b32 s4, v253, 28
	v_readlane_b32 s5, v253, 29
	s_waitcnt vmcnt(0)
	v_add_u32_e32 v16, v16, v2
	s_nop 2
	global_load_dword v3, v193, s[4:5] sc1
	v_readlane_b32 s4, v253, 30
	v_readlane_b32 s5, v253, 31
	s_waitcnt vmcnt(0)
	v_add_u32_e32 v16, v16, v3
	s_nop 2
	global_load_dword v4, v193, s[4:5] sc1
	v_readlane_b32 s4, v253, 32
	v_readlane_b32 s5, v253, 33
	s_waitcnt vmcnt(0)
	v_add_u32_e32 v16, v16, v4
	s_nop 2
	global_load_dword v5, v193, s[4:5] sc1
	v_readlane_b32 s4, v253, 34
	v_readlane_b32 s5, v253, 35
	s_waitcnt vmcnt(0)
	v_add_u32_e32 v16, v16, v5
	s_nop 2
	global_load_dword v6, v193, s[4:5] sc1
	v_readlane_b32 s4, v253, 36
	v_readlane_b32 s5, v253, 37
	s_waitcnt vmcnt(0)
	v_add_u32_e32 v16, v16, v6
	s_nop 2
	global_load_dword v7, v193, s[4:5] sc1
	v_readlane_b32 s4, v253, 38
	v_readlane_b32 s5, v253, 39
	s_waitcnt vmcnt(0)
	v_add_u32_e32 v16, v16, v7
	s_nop 2
	global_load_dword v8, v193, s[4:5] sc1
	v_readlane_b32 s4, v253, 40
	v_readlane_b32 s5, v253, 41
	s_waitcnt vmcnt(0)
	v_add_u32_e32 v16, v16, v8
	s_nop 2
	global_load_dword v9, v193, s[4:5] sc1
	v_readlane_b32 s4, v253, 42
	v_readlane_b32 s5, v253, 43
	s_waitcnt vmcnt(0)
	v_add_u32_e32 v16, v16, v9
	s_nop 2
	global_load_dword v10, v193, s[4:5] sc1
	v_readlane_b32 s4, v253, 44
	v_readlane_b32 s5, v253, 45
	s_waitcnt vmcnt(0)
	v_add_u32_e32 v16, v16, v10
	s_nop 2
	global_load_dword v11, v193, s[4:5] sc1
	v_readlane_b32 s4, v253, 46
	v_readlane_b32 s5, v253, 47
	s_waitcnt vmcnt(0)
	v_add_u32_e32 v16, v16, v11
	s_nop 2
	global_load_dword v12, v193, s[4:5] sc1
	v_readlane_b32 s4, v253, 48
	v_readlane_b32 s5, v253, 49
	s_waitcnt vmcnt(0)
	v_add_u32_e32 v16, v16, v12
	s_nop 2
	global_load_dword v13, v193, s[4:5] sc1
	v_readlane_b32 s4, v253, 50
	v_readlane_b32 s5, v253, 51
	s_waitcnt vmcnt(0)
	v_add_u32_e32 v16, v16, v13
	s_nop 2
	global_load_dword v14, v193, s[4:5] sc1
	v_readlane_b32 s4, v253, 52
	v_readlane_b32 s5, v253, 53
	s_waitcnt vmcnt(0)
	v_add_u32_e32 v16, v16, v14
	s_nop 2
	global_load_dword v15, v193, s[4:5] sc1
	s_mov_b64 s[4:5], -1
	s_waitcnt vmcnt(0)
	v_add_u32_e32 v16, v16, v15
	v_cmp_eq_u32_e32 vcc, s14, v16
	s_cbranch_vccnz .LBB0_3667
	s_and_b32 s4, s15, 0xff
	s_cmp_eq_u32 s4, 0
	s_mov_b64 s[4:5], -1
	s_mov_b64 s[10:11], -1
	s_sleep 0
	s_cbranch_scc0 .LBB0_3672
	v_readlane_b32 s4, v253, 20
	v_readlane_b32 s5, v253, 21
	s_nop 4
	global_load_dword v16, v193, s[4:5] sc1
	s_waitcnt vmcnt(0)
	v_cmp_eq_u32_e32 vcc, 0, v16
	s_cbranch_vccnz .LBB0_3674
	s_mov_b64 s[10:11], 0
	s_mov_b64 s[4:5], -1

.LBB0_3686:
	s_and_b32 s18, s23, 0xff
	s_mov_b64 s[16:17], -1
	s_cmp_lg_u32 s18, 0
	s_mov_b64 s[20:21], -1
	s_sleep 0
	s_cbranch_scc1 .LBB0_3689
	v_readlane_b32 s18, v253, 20
	v_readlane_b32 s19, v253, 21
	s_nop 4
	global_load_dword v0, v193, s[18:19] sc1
	s_waitcnt vmcnt(0)
	v_cmp_eq_u32_e32 vcc, 0, v0
	s_cbranch_vccnz .LBB0_3691
	s_mov_b64 s[20:21], 0
	s_mov_b64 s[18:19], -1

.LBB0_3703:
	s_and_b32 s16, s20, 0xff
	s_mov_b64 s[14:15], -1
	s_cmp_lg_u32 s16, 0
	s_mov_b64 s[18:19], -1
	s_sleep 0
	s_cbranch_scc1 .LBB0_3706
	v_readlane_b32 s16, v253, 20
	v_readlane_b32 s17, v253, 21
	s_nop 4
	global_load_dword v0, v193, s[16:17] sc1
	s_waitcnt vmcnt(0)
	v_cmp_eq_u32_e32 vcc, 0, v0
	s_cbranch_vccnz .LBB0_3708
	s_mov_b64 s[18:19], 0
	s_mov_b64 s[16:17], -1
